# A1 score loop: j=0 fragments prefetched one outer iteration ahead (first iteration before the weight waits), vmcnt waits re-counted
# speedup vs baseline: 1.0026x; 1.0026x over previous
; DI void phaseA1(const Params& p, int vblock, int nvblocks, int ubegin, int uend, char* smem) {
;     ...
;     const int u = 4095 - u0;
;     const int b = u >> 8, q0 = (u & 255) * 8;
;     const size_t tokb = (size_t)b * SEQ;
;     const int qa = ((r >> 2) & 1) * 2 + (r >> 4), ha = (r & 3) + 4 * ((r >> 3) & 1);
;     bf16x8 af0[4], af1[4];
; #pragma unroll
;     for (int ks = 0; ks < 4; ++ks) {
;       af0[ks] = ld16(p.projA + (tokb + q0 + qa) * LDA_A + 640 + ha * 64 + ks * 16 + hh * 8);
;       af1[ks] = ld16(p.projA + (tokb + q0 + 4 + qa) * LDA_A + 640 + ha * 64 + ks * 16 + hh * 8);
;     }
;     float wr0[16], wr1[16];
;     {
;       const float4* sp = (const float4*)(p.small + (tokb + q0 + hh * 2) * 32);
;       const float4 wa = sp[0], wb = sp[1], wc = sp[8], wd = sp[9], we = sp[32], wf = sp[33], wg = sp[40], wh = sp[41];
;       __builtin_amdgcn_sched_barrier(0);
;       const float cs = 0.044194173824159216f;
;       wr0[0] = wa.x * cs; wr0[1] = wa.y * cs; wr0[2] = wa.z * cs; wr0[3] = wa.w * cs; wr0[4] = wb.x * cs; wr0[5] = wb.y * cs; wr0[6] = wb.z * cs; wr0[7] = wb.w * cs;
;       wr0[8] = wc.x * cs; wr0[9] = wc.y * cs; wr0[10] = wc.z * cs; wr0[11] = wc.w * cs; wr0[12] = wd.x * cs; wr0[13] = wd.y * cs; wr0[14] = wd.z * cs; wr0[15] = wd.w * cs;
;       wr1[0] = we.x * cs; wr1[1] = we.y * cs; wr1[2] = we.z * cs; wr1[3] = we.w * cs; wr1[4] = wf.x * cs; wr1[5] = wf.y * cs; wr1[6] = wf.z * cs; wr1[7] = wf.w * cs;
;       wr1[8] = wg.x * cs; wr1[9] = wg.y * cs; wr1[10] = wg.z * cs; wr1[11] = wg.w * cs; wr1[12] = wh.x * cs; wr1[13] = wh.y * cs; wr1[14] = wh.z * cs; wr1[15] = wh.w * cs;
;     }
;     const int nt = (q0 + 7) / 32 + 1;
;     const bf16_t* kib = p.kidxF + (size_t)b * 64 * 2048 + (hh * 32 + r) * 8;
; #pragma unroll 1
;     for (int kb = wid; kb < nt; kb += 16) {
;       bf16x8 kf[4][4];
; #pragma unroll
;       for (int j = 0; j < 4; ++j) {
;         const int kt = kb + 4 * j < nt ? kb + 4 * j : kb;
;         const bf16_t* q_ = kib + (size_t)kt * 2048;
.LBB0_343:
	s_sub_i32 s2, 0xfff, s11
	s_lshl_b32 s16, s2, 3
	s_lshr_b32 s14, s2, 8
	s_and_b32 s88, s16, 0x7f8
	v_readlane_b32 s36, v252, 57
	s_lshl_b64 s[12:13], s[14:15], 11
	v_or_b32_e32 v2, s88, v116
	v_readlane_b32 s44, v253, 1
	v_readlane_b32 s45, v253, 2
	v_or_b32_e32 v4, s12, v2
	s_movk_i32 s2, 0xd00
	v_mov_b64_e32 v[2:3], s[44:45]
	v_mad_u64_u32 v[2:3], s[2:3], v4, s2, v[2:3]
	v_mad_u32_u24 v3, s13, v238, v3
	v_lshl_add_u64 v[2:3], v[2:3], 0, v[0:1]
	v_mov_b32_e32 v111, v1
	v_lshl_add_u64 v[2:3], v[2:3], 0, v[110:111]
	s_mov_b64 s[2:3], 0x3900
	v_add_co_u32_e32 v6, vcc, s81, v2
	s_or_b32 s12, s12, s88
	v_lshl_add_u64 v[4:5], v[2:3], 0, s[2:3]
	v_addc_co_u32_e32 v7, vcc, 0, v3, vcc
	global_load_dwordx4 v[34:37], v[2:3], off offset:1280
	global_load_dwordx4 v[38:41], v[2:3], off offset:1312
	global_load_dwordx4 v[42:45], v[4:5], off offset:32
	global_load_dwordx4 v[46:49], v[4:5], off offset:64
	global_load_dwordx4 v[50:53], v[2:3], off offset:1344
	global_load_dwordx4 v[54:57], v[2:3], off offset:1376
	global_load_dwordx4 v[58:61], v[6:7], off offset:2304
	global_load_dwordx4 v[62:65], v[4:5], off offset:96
	v_mov_b32_e32 v3, s13
	v_or_b32_e32 v2, s12, v100
	v_readlane_b32 s50, v253, 7
	v_readlane_b32 s51, v253, 8
	v_lshlrev_b64 v[2:3], 7, v[2:3]
	v_readlane_b32 s40, v252, 61
	v_lshl_add_u64 v[6:7], s[50:51], 0, v[2:3]
	global_load_dwordx4 v[26:29], v[6:7], off offset:16
	global_load_dwordx4 v[30:33], v[6:7], off
	global_load_dwordx4 v[18:21], v[6:7], off offset:144
	global_load_dwordx4 v[22:25], v[6:7], off offset:128
	global_load_dwordx4 v[10:13], v[6:7], off offset:528
	global_load_dwordx4 v[14:17], v[6:7], off offset:512
	global_load_dwordx4 v[2:5], v[6:7], off offset:656
	s_nop 0
	global_load_dwordx4 v[6:9], v[6:7], off offset:640
	v_readlane_b32 s41, v252, 62
	v_readlane_b32 s42, v252, 63
	s_movk_i32 s42, 0x100
	s_mov_b64 s[40:41], 0x10000
	v_readlane_b32 s37, v252, 58
	v_readlane_b32 s38, v252, 59
	v_readlane_b32 s39, v252, 60
	v_readlane_b32 s43, v253, 0
	v_readlane_b32 s46, v253, 3
	v_readlane_b32 s47, v253, 4
	v_readlane_b32 s48, v253, 5
	v_readlane_b32 s49, v253, 6
	s_bfe_u32 s89, s16, 0x60005
	v_cmp_ge_i32_e32 vcc, s89, v98
	s_and_saveexec_b64 s[84:85], vcc
	s_mov_b32 s17, 0xff00ff
	s_mov_b32 s18, 0xf0f0f0f
	s_mov_b32 s19, 0x33333333
	s_mov_b32 s20, 0x55555555
	s_cbranch_execz .LBB0_352
	s_lshl_b64 s[2:3], s[10:11], 10
	s_and_b32 s3, s3, 0x3ff
	s_and_b32 s2, s2, 0xfffc0000
	v_lshl_add_u64 v[112:113], v[108:109], 0, s[2:3]
	global_load_dwordx4 v[216:219], v[112:113], off offset:-3072
	global_load_dwordx4 v[220:223], v[112:113], off offset:-2048
	global_load_dwordx4 v[224:227], v[112:113], off offset:-1024
	global_load_dwordx4 v[240:243], v[112:113], off
	s_lshl_b64 s[2:3], s[14:15], 18
	s_waitcnt vmcnt(10)
	v_mul_f32_e32 v111, 0x3d3504f3, v30
	v_mul_f32_e32 v119, 0x3d3504f3, v31
	v_mul_f32_e32 v120, 0x3d3504f3, v32
	v_mul_f32_e32 v121, 0x3d3504f3, v33
	v_mul_f32_e32 v122, 0x3d3504f3, v26
	v_mul_f32_e32 v123, 0x3d3504f3, v27
	v_mul_f32_e32 v124, 0x3d3504f3, v28
	v_mul_f32_e32 v125, 0x3d3504f3, v29
	s_waitcnt vmcnt(8)
	v_mul_f32_e32 v126, 0x3d3504f3, v22
	v_mul_f32_e32 v127, 0x3d3504f3, v23
	v_mul_f32_e32 v128, 0x3d3504f3, v24
	v_mul_f32_e32 v129, 0x3d3504f3, v25
	v_mul_f32_e32 v130, 0x3d3504f3, v18
	v_mul_f32_e32 v131, 0x3d3504f3, v19
	v_mul_f32_e32 v132, 0x3d3504f3, v20
	v_mul_f32_e32 v133, 0x3d3504f3, v21
	s_waitcnt vmcnt(6)
	v_mul_f32_e32 v134, 0x3d3504f3, v14
	v_mul_f32_e32 v135, 0x3d3504f3, v15
	v_mul_f32_e32 v136, 0x3d3504f3, v16
	v_mul_f32_e32 v137, 0x3d3504f3, v17
	v_mul_f32_e32 v138, 0x3d3504f3, v10
	v_mul_f32_e32 v139, 0x3d3504f3, v11
	v_mul_f32_e32 v140, 0x3d3504f3, v12
	v_mul_f32_e32 v141, 0x3d3504f3, v13
	s_waitcnt vmcnt(4)
	v_mul_f32_e32 v142, 0x3d3504f3, v6
	v_mul_f32_e32 v143, 0x3d3504f3, v7
	v_mul_f32_e32 v144, 0x3d3504f3, v8
	v_mul_f32_e32 v145, 0x3d3504f3, v9
	v_mul_f32_e32 v146, 0x3d3504f3, v2
	v_mul_f32_e32 v147, 0x3d3504f3, v3
	v_mul_f32_e32 v148, 0x3d3504f3, v4
	v_mul_f32_e32 v149, 0x3d3504f3, v5
	v_lshl_add_u64 v[114:115], v[104:105], 0, s[2:3]
	s_mov_b64 s[86:87], 0
	v_mov_b32_e32 v150, v118
	v_mov_b32_e32 v151, v98
	s_branch .LBB0_346

; #define MFMA32(a, b, c) __builtin_amdgcn_mfma_f32_32x32x16_bf16((a), (b), (c), 0, 0, 0)
; DI void phaseA1(const Params& p, int vblock, int nvblocks, int ubegin, int uend, char* smem) {
;     ...
;     for (int kb = wid; kb < nt; kb += 16) {
;       bf16x8 kf[4][4];
; #pragma unroll
;       for (int j = 0; j < 4; ++j) {
;         const int kt = kb + 4 * j < nt ? kb + 4 * j : kb;
;         const bf16_t* q_ = kib + (size_t)kt * 2048;
;         kf[j][0] = ld16(q_); kf[j][1] = ld16(q_ + 512); kf[j][2] = ld16(q_ + 1024); kf[j][3] = ld16(q_ + 1536);
;       }
; #pragma unroll
;       for (int j = 0; j < 4; ++j) {
;         const int kt = kb + 4 * j;
;         if (kt < nt) {
;           f32x16 s0, s1;
; #pragma unroll
;           for (int e = 0; e < 16; ++e) { s0[e] = 0.f; s1[e] = 0.f; }
; #pragma unroll
;           for (int ks = 0; ks < 4; ++ks) { s0 = MFMA32(af0[ks], kf[j][ks], s0); s1 = MFMA32(af1[ks], kf[j][ks], s1); }
;           float a0 = 0.f, a1 = 0.f, a2 = 0.f, a3 = 0.f;
; #pragma unroll
;           for (int e = 0; e < 8; ++e) {
;             a0 += wr0[e] * fmaxf(s0[e], 0.f); a1 += wr0[8 + e] * fmaxf(s0[8 + e], 0.f);
;             a2 += wr1[e] * fmaxf(s1[e], 0.f); a3 += wr1[8 + e] * fmaxf(s1[8 + e], 0.f);
;           }
;           const int key = kt * 32 + r;
;           sc[(hh * 2 + 0) * 2048 + key] = a0 + 0.0f;
;           sc[(hh * 2 + 1) * 2048 + key] = a1 + 0.0f;
;           sc[(4 + hh * 2 + 0) * 2048 + key] = a2 + 0.0f;
;           sc[(4 + hh * 2 + 1) * 2048 + key] = a3 + 0.0f;
.LBB0_346:
	v_add_u32_e32 v152, 4, v151
	v_cmp_lt_i32_e64 s[72:73], s89, v152
	v_cmp_ge_i32_e64 s[74:75], s89, v152
	s_nop 0
	v_cndmask_b32_e64 v172, v152, v151, s[72:73]
	v_ashrrev_i32_e32 v173, 31, v172
	v_lshlrev_b64 v[172:173], 12, v[172:173]
	v_lshl_add_u64 v[172:173], v[114:115], 0, v[172:173]
	global_load_dwordx4 v[190:193], v[172:173], off
	global_load_dwordx4 v[194:197], v[172:173], off offset:1024
	global_load_dwordx4 v[198:201], v[172:173], off offset:2048
	global_load_dwordx4 v[202:205], v[172:173], off offset:3072
	s_waitcnt vmcnt(7)
	v_mfma_f32_32x32x16_bf16 v[18:33], v[34:37], v[216:219], 0
	v_mfma_f32_32x32x16_bf16 v[2:17], v[58:61], v[216:219], 0
	s_waitcnt vmcnt(6)
	v_mfma_f32_32x32x16_bf16 v[18:33], v[38:41], v[220:223], v[18:33]
	v_mfma_f32_32x32x16_bf16 v[2:17], v[42:45], v[220:223], v[2:17]
	v_add_u32_e32 v66, 8, v151
	v_add_u32_e32 v67, 12, v151
	v_cmp_lt_i32_e32 vcc, s89, v66
	v_cmp_lt_i32_e64 s[2:3], s89, v67
	v_cmp_ge_i32_e64 s[70:71], s89, v66
	v_cndmask_b32_e32 v66, v66, v151, vcc
	v_cndmask_b32_e64 v68, v67, v151, s[2:3]
	v_cmp_ge_i32_e32 vcc, s89, v67
	v_ashrrev_i32_e32 v67, 31, v66
	v_ashrrev_i32_e32 v69, 31, v68
	v_lshlrev_b64 v[66:67], 12, v[66:67]
	v_lshlrev_b64 v[68:69], 12, v[68:69]
	v_lshl_add_u64 v[66:67], v[114:115], 0, v[66:67]
	v_lshl_add_u64 v[68:69], v[114:115], 0, v[68:69]
	s_waitcnt vmcnt(5)
	v_mfma_f32_32x32x16_bf16 v[18:33], v[50:53], v[224:227], v[18:33]
	v_mfma_f32_32x32x16_bf16 v[2:17], v[46:49], v[224:227], v[2:17]
	global_load_dwordx4 v[94:97], v[66:67], off
	global_load_dwordx4 v[90:93], v[66:67], off offset:1024
	global_load_dwordx4 v[86:89], v[66:67], off offset:2048
	global_load_dwordx4 v[82:85], v[66:67], off offset:3072
	global_load_dwordx4 v[78:81], v[68:69], off
	global_load_dwordx4 v[74:77], v[68:69], off offset:1024
	global_load_dwordx4 v[70:73], v[68:69], off offset:2048
	s_nop 0
	global_load_dwordx4 v[66:69], v[68:69], off offset:3072
	s_waitcnt vmcnt(12)
	v_mfma_f32_32x32x16_bf16 v[18:33], v[54:57], v[240:243], v[18:33]
	v_mfma_f32_32x32x16_bf16 v[2:17], v[62:65], v[240:243], v[2:17]
	v_add_u32_e32 v174, 16, v151
	v_min_i32_e32 v174, s89, v174
	v_ashrrev_i32_e32 v175, 31, v174
	v_lshlrev_b64 v[174:175], 12, v[174:175]
	v_lshl_add_u64 v[174:175], v[114:115], 0, v[174:175]
	global_load_dwordx4 v[216:219], v[174:175], off
	global_load_dwordx4 v[220:223], v[174:175], off offset:1024
	global_load_dwordx4 v[224:227], v[174:175], off offset:2048
	global_load_dwordx4 v[240:243], v[174:175], off offset:3072
	s_nop 10
	v_max_f32_e32 v18, v18, v18
	v_max_f32_e32 v19, v19, v19
	v_max_f32_e32 v18, 0, v18
	v_max_f32_e32 v26, v26, v26
	v_max_f32_e32 v20, v20, v20
	v_max_f32_e32 v19, 0, v19
	v_fma_f32 v18, v111, v18, 0
	v_max_f32_e32 v27, v27, v27
	v_max_f32_e32 v21, v21, v21
	v_max_f32_e32 v26, 0, v26
	v_max_f32_e32 v20, 0, v20
	v_fmac_f32_e32 v18, v119, v19
	v_max_f32_e32 v2, v2, v2
	v_max_f32_e32 v28, v28, v28
	v_max_f32_e32 v22, v22, v22
	v_max_f32_e32 v27, 0, v27
	v_max_f32_e32 v21, 0, v21
	v_fma_f32 v26, v126, v26, 0
	v_fmac_f32_e32 v18, v120, v20
	v_max_f32_e32 v3, v3, v3
	v_max_f32_e32 v29, v29, v29
	v_max_f32_e32 v23, v23, v23
	v_max_f32_e32 v2, 0, v2
	v_max_f32_e32 v28, 0, v28
	v_max_f32_e32 v22, 0, v22
	v_fmac_f32_e32 v26, v127, v27
	v_fmac_f32_e32 v18, v121, v21
	v_max_f32_e32 v10, v10, v10
	v_max_f32_e32 v4, v4, v4
	v_max_f32_e32 v30, v30, v30
	v_max_f32_e32 v24, v24, v24
	v_max_f32_e32 v3, 0, v3
	v_max_f32_e32 v29, 0, v29
	v_max_f32_e32 v23, 0, v23
	v_fma_f32 v2, v134, v2, 0
	v_fmac_f32_e32 v26, v128, v28
	v_fmac_f32_e32 v18, v122, v22
	v_max_f32_e32 v11, v11, v11
	v_max_f32_e32 v5, v5, v5
	v_max_f32_e32 v31, v31, v31
	v_max_f32_e32 v10, 0, v10
	v_max_f32_e32 v4, 0, v4
	v_max_f32_e32 v30, 0, v30
	v_max_f32_e32 v24, 0, v24
	v_fmac_f32_e32 v2, v135, v3
	v_fmac_f32_e32 v26, v129, v29
	v_fmac_f32_e32 v18, v123, v23
	v_max_f32_e32 v3, v25, v25
	v_max_f32_e32 v12, v12, v12
	v_max_f32_e32 v6, v6, v6
	v_max_f32_e32 v32, v32, v32
	v_max_f32_e32 v11, 0, v11
	v_max_f32_e32 v5, 0, v5
	v_max_f32_e32 v31, 0, v31
	v_fma_f32 v10, v142, v10, 0
	v_fmac_f32_e32 v2, v136, v4
	v_fmac_f32_e32 v26, v130, v30
	v_fmac_f32_e32 v18, v124, v24
	v_max_f32_e32 v3, 0, v3
	v_max_f32_e32 v13, v13, v13
	v_max_f32_e32 v7, v7, v7
	v_max_f32_e32 v12, 0, v12
	v_max_f32_e32 v6, 0, v6
	v_max_f32_e32 v32, 0, v32
	v_fmac_f32_e32 v10, v143, v11
	v_fmac_f32_e32 v2, v137, v5
	v_fmac_f32_e32 v26, v131, v31
	v_fmac_f32_e32 v18, v125, v3
	v_max_f32_e32 v3, v33, v33
	v_max_f32_e32 v14, v14, v14
	v_max_f32_e32 v8, v8, v8
	v_max_f32_e32 v13, 0, v13
	v_max_f32_e32 v7, 0, v7
	v_fmac_f32_e32 v10, v144, v12
	v_fmac_f32_e32 v2, v138, v6
	v_fmac_f32_e32 v26, v132, v32
	v_max_f32_e32 v3, 0, v3
	v_max_f32_e32 v15, v15, v15
	v_max_f32_e32 v14, 0, v14
	v_max_f32_e32 v8, 0, v8
	v_fmac_f32_e32 v10, v145, v13
	v_fmac_f32_e32 v2, v139, v7
	v_fmac_f32_e32 v26, v133, v3
	v_max_f32_e32 v3, v9, v9
	v_max_f32_e32 v16, v16, v16
	v_max_f32_e32 v15, 0, v15
	v_fmac_f32_e32 v10, v146, v14
	v_fmac_f32_e32 v2, v140, v8
	v_max_f32_e32 v3, 0, v3
	v_max_f32_e32 v16, 0, v16
	v_fmac_f32_e32 v10, v147, v15
	v_fmac_f32_e32 v2, v141, v3
	v_max_f32_e32 v3, v17, v17
	v_fmac_f32_e32 v10, v148, v16
	v_max_f32_e32 v3, 0, v3
	v_fmac_f32_e32 v10, v149, v3
	v_add_f32_e32 v3, 0, v18
	v_add_f32_e32 v4, 0, v26
	ds_write2st64_b32 v150, v3, v4 offset1:32
	v_add_f32_e32 v2, 0, v2
	v_add_f32_e32 v3, 0, v10
	ds_write2st64_b32 v150, v2, v3 offset0:128 offset1:160
	s_and_saveexec_b64 s[2:3], s[74:75]
	s_cbranch_execz .LBB0_349
; #define MFMA32(a, b, c) __builtin_amdgcn_mfma_f32_32x32x16_bf16((a), (b), (c), 0, 0, 0)
; DI void phaseA1(const Params& p, int vblock, int nvblocks, int ubegin, int uend, char* smem) {
;     ...
; #pragma unroll
;       for (int j = 0; j < 4; ++j) {
;         const int kt = kb + 4 * j;
;         if (kt < nt) {
;           f32x16 s0, s1;
; #pragma unroll
;           for (int e = 0; e < 16; ++e) { s0[e] = 0.f; s1[e] = 0.f; }
; #pragma unroll
;           for (int ks = 0; ks < 4; ++ks) { s0 = MFMA32(af0[ks], kf[j][ks], s0); s1 = MFMA32(af1[ks], kf[j][ks], s1); }
;           float a0 = 0.f, a1 = 0.f, a2 = 0.f, a3 = 0.f;
; #pragma unroll
;           for (int e = 0; e < 8; ++e) {
;             a0 += wr0[e] * fmaxf(s0[e], 0.f); a1 += wr0[8 + e] * fmaxf(s0[8 + e], 0.f);
;             a2 += wr1[e] * fmaxf(s1[e], 0.f); a3 += wr1[8 + e] * fmaxf(s1[8 + e], 0.f);
;           }
;           const int key = kt * 32 + r;
;           sc[(hh * 2 + 0) * 2048 + key] = a0 + 0.0f;
;           sc[(hh * 2 + 1) * 2048 + key] = a1 + 0.0f;
;           sc[(4 + hh * 2 + 0) * 2048 + key] = a2 + 0.0f;
;           sc[(4 + hh * 2 + 1) * 2048 + key] = a3 + 0.0f;
	s_waitcnt vmcnt(12)
	v_mfma_f32_32x32x16_bf16 v[18:33], v[34:37], v[190:193], 0
	v_mfma_f32_32x32x16_bf16 v[2:17], v[58:61], v[190:193], 0
	v_mfma_f32_32x32x16_bf16 v[18:33], v[38:41], v[194:197], v[18:33]
	v_mfma_f32_32x32x16_bf16 v[2:17], v[42:45], v[194:197], v[2:17]
	v_mfma_f32_32x32x16_bf16 v[18:33], v[50:53], v[198:201], v[18:33]
	v_mfma_f32_32x32x16_bf16 v[2:17], v[46:49], v[198:201], v[2:17]
	v_mfma_f32_32x32x16_bf16 v[18:33], v[54:57], v[202:205], v[18:33]
	s_nop 11
	v_max_f32_e32 v18, v18, v18
	v_mfma_f32_32x32x16_bf16 v[2:17], v[62:65], v[202:205], v[2:17]
	v_max_f32_e32 v26, v26, v26
	v_max_f32_e32 v19, v19, v19
	v_max_f32_e32 v27, v27, v27
	v_max_f32_e32 v18, 0, v18
	v_max_f32_e32 v26, 0, v26
	v_max_f32_e32 v20, v20, v20
	v_max_f32_e32 v28, v28, v28
	s_nop 4
	v_max_f32_e32 v2, v2, v2
	v_max_f32_e32 v10, v10, v10
	v_max_f32_e32 v3, v3, v3
	v_max_f32_e32 v11, v11, v11
	v_max_f32_e32 v2, 0, v2
	v_max_f32_e32 v10, 0, v10
	v_max_f32_e32 v19, 0, v19
	v_max_f32_e32 v27, 0, v27
	v_fma_f32 v18, v111, v18, 0
	v_fma_f32 v26, v126, v26, 0
	v_max_f32_e32 v4, v4, v4
	v_max_f32_e32 v12, v12, v12
	v_max_f32_e32 v21, v21, v21
	v_max_f32_e32 v29, v29, v29
	v_max_f32_e32 v3, 0, v3
	v_max_f32_e32 v11, 0, v11
	v_max_f32_e32 v20, 0, v20
	v_max_f32_e32 v28, 0, v28
	v_fma_f32 v2, v134, v2, 0
	v_fma_f32 v10, v142, v10, 0
	v_fmac_f32_e32 v18, v119, v19
	v_fmac_f32_e32 v26, v127, v27
	v_max_f32_e32 v5, v5, v5
	v_max_f32_e32 v13, v13, v13
	v_max_f32_e32 v22, v22, v22
	v_max_f32_e32 v30, v30, v30
	v_max_f32_e32 v4, 0, v4
	v_max_f32_e32 v12, 0, v12
	v_max_f32_e32 v21, 0, v21
	v_max_f32_e32 v29, 0, v29
	v_fmac_f32_e32 v2, v135, v3
	v_fmac_f32_e32 v10, v143, v11
	v_fmac_f32_e32 v18, v120, v20
	v_fmac_f32_e32 v26, v128, v28
	v_max_f32_e32 v6, v6, v6
	v_max_f32_e32 v14, v14, v14
	v_max_f32_e32 v23, v23, v23
	v_max_f32_e32 v31, v31, v31
	v_max_f32_e32 v5, 0, v5
	v_max_f32_e32 v13, 0, v13
	v_max_f32_e32 v22, 0, v22
	v_max_f32_e32 v30, 0, v30
	v_fmac_f32_e32 v2, v136, v4
	v_fmac_f32_e32 v10, v144, v12
	v_fmac_f32_e32 v18, v121, v21
	v_fmac_f32_e32 v26, v129, v29
	v_max_f32_e32 v7, v7, v7
	v_max_f32_e32 v15, v15, v15
	v_max_f32_e32 v24, v24, v24
	v_max_f32_e32 v32, v32, v32
	v_max_f32_e32 v6, 0, v6
	v_max_f32_e32 v14, 0, v14
	v_max_f32_e32 v23, 0, v23
	v_max_f32_e32 v31, 0, v31
	v_fmac_f32_e32 v2, v137, v5
	v_fmac_f32_e32 v10, v145, v13
	v_fmac_f32_e32 v18, v122, v22
	v_fmac_f32_e32 v26, v130, v30
	v_max_f32_e32 v8, v8, v8
	v_max_f32_e32 v16, v16, v16
	v_max_f32_e32 v25, v25, v25
	v_max_f32_e32 v33, v33, v33
	v_max_f32_e32 v7, 0, v7
	v_max_f32_e32 v15, 0, v15
	v_max_f32_e32 v24, 0, v24
	v_max_f32_e32 v32, 0, v32
	v_fmac_f32_e32 v2, v138, v6
	v_fmac_f32_e32 v10, v146, v14
	v_fmac_f32_e32 v18, v123, v23
	v_fmac_f32_e32 v26, v131, v31
	v_max_f32_e32 v9, v9, v9
	v_max_f32_e32 v17, v17, v17
	v_max_f32_e32 v8, 0, v8
	v_max_f32_e32 v16, 0, v16
	v_max_f32_e32 v25, 0, v25
	v_max_f32_e32 v33, 0, v33
	v_fmac_f32_e32 v2, v139, v7
	v_fmac_f32_e32 v10, v147, v15
	v_fmac_f32_e32 v18, v124, v24
	v_fmac_f32_e32 v26, v132, v32
	v_max_f32_e32 v9, 0, v9
	v_max_f32_e32 v17, 0, v17
	v_fmac_f32_e32 v2, v140, v8
	v_fmac_f32_e32 v10, v148, v16
	v_fmac_f32_e32 v18, v125, v25
	v_fmac_f32_e32 v26, v133, v33
	v_fmac_f32_e32 v2, v141, v9
	v_fmac_f32_e32 v10, v149, v17
	v_add_f32_e32 v3, 0, v18
	v_add_f32_e32 v4, 0, v26
	v_add_f32_e32 v2, 0, v2
	v_add_f32_e32 v5, 0, v10
	ds_write2st64_b32 v150, v3, v4 offset0:2 offset1:34
	ds_write2st64_b32 v150, v2, v5 offset0:130 offset1:162
	s_or_b64 exec, exec, s[2:3]
	s_and_saveexec_b64 s[2:3], s[70:71]
	s_cbranch_execnz .LBB0_350

; #define MFMA32(a, b, c) __builtin_amdgcn_mfma_f32_32x32x16_bf16((a), (b), (c), 0, 0, 0)
; DI void phaseA1(const Params& p, int vblock, int nvblocks, int ubegin, int uend, char* smem) {
;     ...
; #pragma unroll
;       for (int j = 0; j < 4; ++j) {
;         const int kt = kb + 4 * j;
;         if (kt < nt) {
;           f32x16 s0, s1;
; #pragma unroll
;           for (int e = 0; e < 16; ++e) { s0[e] = 0.f; s1[e] = 0.f; }
; #pragma unroll
;           for (int ks = 0; ks < 4; ++ks) { s0 = MFMA32(af0[ks], kf[j][ks], s0); s1 = MFMA32(af1[ks], kf[j][ks], s1); }
;           float a0 = 0.f, a1 = 0.f, a2 = 0.f, a3 = 0.f;
; #pragma unroll
;           for (int e = 0; e < 8; ++e) {
;             a0 += wr0[e] * fmaxf(s0[e], 0.f); a1 += wr0[8 + e] * fmaxf(s0[8 + e], 0.f);
;             a2 += wr1[e] * fmaxf(s1[e], 0.f); a3 += wr1[8 + e] * fmaxf(s1[8 + e], 0.f);
;           }
;           const int key = kt * 32 + r;
;           sc[(hh * 2 + 0) * 2048 + key] = a0 + 0.0f;
;           sc[(hh * 2 + 1) * 2048 + key] = a1 + 0.0f;
;           sc[(4 + hh * 2 + 0) * 2048 + key] = a2 + 0.0f;
;           sc[(4 + hh * 2 + 1) * 2048 + key] = a3 + 0.0f;
.LBB0_350:
	s_waitcnt vmcnt(11)
	v_mfma_f32_32x32x16_bf16 v[2:17], v[58:61], v[94:97], 0
	v_mfma_f32_32x32x16_bf16 v[18:33], v[34:37], v[94:97], 0
	s_waitcnt vmcnt(10)
	v_mfma_f32_32x32x16_bf16 v[2:17], v[42:45], v[90:93], v[2:17]
	v_mfma_f32_32x32x16_bf16 v[18:33], v[38:41], v[90:93], v[18:33]
	s_waitcnt vmcnt(9)
	v_mfma_f32_32x32x16_bf16 v[2:17], v[46:49], v[86:89], v[2:17]
	v_mfma_f32_32x32x16_bf16 v[18:33], v[50:53], v[86:89], v[18:33]
	s_waitcnt vmcnt(8)
	v_mfma_f32_32x32x16_bf16 v[2:17], v[62:65], v[82:85], v[2:17]
	v_mfma_f32_32x32x16_bf16 v[18:33], v[54:57], v[82:85], v[18:33]
	s_nop 10
	v_max_f32_e32 v2, v2, v2
	v_max_f32_e32 v2, 0, v2
	v_max_f32_e32 v3, v3, v3
	v_fma_f32 v2, v134, v2, 0
	v_max_f32_e32 v10, v10, v10
	v_max_f32_e32 v3, 0, v3
	v_max_f32_e32 v10, 0, v10
	v_max_f32_e32 v18, v18, v18
	v_fmac_f32_e32 v2, v135, v3
	v_max_f32_e32 v3, v11, v11
	v_max_f32_e32 v18, 0, v18
	v_fma_f32 v10, v142, v10, 0
	v_max_f32_e32 v19, v19, v19
	v_max_f32_e32 v3, 0, v3
	v_fma_f32 v18, v111, v18, 0
	v_max_f32_e32 v26, v26, v26
	v_max_f32_e32 v19, 0, v19
	v_fmac_f32_e32 v10, v143, v3
	v_max_f32_e32 v3, v20, v20
	v_max_f32_e32 v26, 0, v26
	v_fmac_f32_e32 v18, v119, v19
	v_max_f32_e32 v19, v27, v27
	v_max_f32_e32 v3, 0, v3
	v_fma_f32 v26, v126, v26, 0
	v_max_f32_e32 v19, 0, v19
	v_fmac_f32_e32 v18, v120, v3
	v_max_f32_e32 v3, v28, v28
	v_fmac_f32_e32 v26, v127, v19
	v_max_f32_e32 v3, 0, v3
	v_fmac_f32_e32 v26, v128, v3
	v_max_f32_e32 v3, v4, v4
	v_max_f32_e32 v3, 0, v3
	v_fmac_f32_e32 v2, v136, v3
	v_max_f32_e32 v3, v12, v12
	v_max_f32_e32 v3, 0, v3
	v_fmac_f32_e32 v10, v144, v3
	v_max_f32_e32 v3, v21, v21
	v_max_f32_e32 v3, 0, v3
	v_fmac_f32_e32 v18, v121, v3
	v_max_f32_e32 v3, v29, v29
	v_max_f32_e32 v3, 0, v3
	v_fmac_f32_e32 v26, v129, v3
	v_max_f32_e32 v3, v5, v5
	v_max_f32_e32 v3, 0, v3
	v_fmac_f32_e32 v2, v137, v3
	v_max_f32_e32 v3, v13, v13
	v_max_f32_e32 v3, 0, v3
	v_fmac_f32_e32 v10, v145, v3
	v_max_f32_e32 v3, v22, v22
	v_max_f32_e32 v3, 0, v3
	v_fmac_f32_e32 v18, v122, v3
	v_max_f32_e32 v3, v30, v30
	v_max_f32_e32 v3, 0, v3
	v_fmac_f32_e32 v26, v130, v3
	v_max_f32_e32 v3, v6, v6
	v_max_f32_e32 v3, 0, v3
	v_fmac_f32_e32 v2, v138, v3
	v_max_f32_e32 v3, v14, v14
	v_max_f32_e32 v3, 0, v3
	v_fmac_f32_e32 v10, v146, v3
	v_max_f32_e32 v3, v23, v23
	v_max_f32_e32 v3, 0, v3
	v_fmac_f32_e32 v18, v123, v3
	v_max_f32_e32 v3, v31, v31
	v_max_f32_e32 v3, 0, v3
	v_fmac_f32_e32 v26, v131, v3
	v_max_f32_e32 v3, v7, v7
	v_max_f32_e32 v3, 0, v3
	v_fmac_f32_e32 v2, v139, v3
	v_max_f32_e32 v3, v15, v15
	v_max_f32_e32 v3, 0, v3
	v_fmac_f32_e32 v10, v147, v3
	v_max_f32_e32 v3, v24, v24
	v_max_f32_e32 v3, 0, v3
	v_fmac_f32_e32 v18, v124, v3
	v_max_f32_e32 v3, v32, v32
	v_max_f32_e32 v3, 0, v3
	v_fmac_f32_e32 v26, v132, v3
	v_max_f32_e32 v3, v8, v8
	v_max_f32_e32 v3, 0, v3
	v_fmac_f32_e32 v2, v140, v3
	v_max_f32_e32 v3, v16, v16
	v_max_f32_e32 v3, 0, v3
	v_fmac_f32_e32 v10, v148, v3
	v_max_f32_e32 v3, v25, v25
	v_max_f32_e32 v3, 0, v3
	v_fmac_f32_e32 v18, v125, v3
	v_max_f32_e32 v3, v33, v33
	v_max_f32_e32 v3, 0, v3
	v_fmac_f32_e32 v26, v133, v3
	v_max_f32_e32 v3, v9, v9
	v_max_f32_e32 v3, 0, v3
	v_fmac_f32_e32 v2, v141, v3
	v_max_f32_e32 v3, v17, v17
	v_max_f32_e32 v3, 0, v3
	v_fmac_f32_e32 v10, v149, v3
	v_add_f32_e32 v3, 0, v18
	v_add_f32_e32 v4, 0, v26
	ds_write2st64_b32 v150, v3, v4 offset0:4 offset1:36
	v_add_f32_e32 v2, 0, v2
	v_add_f32_e32 v3, 0, v10
	ds_write2st64_b32 v150, v2, v3 offset0:132 offset1:164
	s_or_b64 exec, exec, s[2:3]
	s_and_saveexec_b64 s[2:3], vcc
	s_cbranch_execz .LBB0_345
.LBB0_351:
	s_waitcnt vmcnt(7)
	v_mfma_f32_32x32x16_bf16 v[2:17], v[58:61], v[78:81], 0
	v_mfma_f32_32x32x16_bf16 v[18:33], v[34:37], v[78:81], 0
	s_waitcnt vmcnt(6)
	v_mfma_f32_32x32x16_bf16 v[2:17], v[42:45], v[74:77], v[2:17]
	v_mfma_f32_32x32x16_bf16 v[18:33], v[38:41], v[74:77], v[18:33]
	s_waitcnt vmcnt(5)
	v_mfma_f32_32x32x16_bf16 v[2:17], v[46:49], v[70:73], v[2:17]
	v_mfma_f32_32x32x16_bf16 v[18:33], v[50:53], v[70:73], v[18:33]
	s_waitcnt vmcnt(4)
	v_mfma_f32_32x32x16_bf16 v[2:17], v[62:65], v[66:69], v[2:17]
	v_mfma_f32_32x32x16_bf16 v[18:33], v[54:57], v[66:69], v[18:33]
	s_nop 10
	v_max_f32_e32 v2, v2, v2
	v_max_f32_e32 v2, 0, v2
	v_max_f32_e32 v3, v3, v3
	v_fma_f32 v2, v134, v2, 0
	v_max_f32_e32 v10, v10, v10
	v_max_f32_e32 v3, 0, v3
	v_max_f32_e32 v10, 0, v10
	v_max_f32_e32 v18, v18, v18
	v_fmac_f32_e32 v2, v135, v3
	v_max_f32_e32 v3, v11, v11
	v_max_f32_e32 v18, 0, v18
	v_fma_f32 v10, v142, v10, 0
	v_max_f32_e32 v19, v19, v19
	v_max_f32_e32 v3, 0, v3
	v_fma_f32 v18, v111, v18, 0
	v_max_f32_e32 v26, v26, v26
	v_max_f32_e32 v19, 0, v19
	v_fmac_f32_e32 v10, v143, v3
	v_max_f32_e32 v3, v20, v20
	v_max_f32_e32 v26, 0, v26
	v_fmac_f32_e32 v18, v119, v19
	v_max_f32_e32 v19, v27, v27
	v_max_f32_e32 v3, 0, v3
	v_fma_f32 v26, v126, v26, 0
	v_max_f32_e32 v19, 0, v19
	v_fmac_f32_e32 v18, v120, v3
	v_max_f32_e32 v3, v28, v28
	v_fmac_f32_e32 v26, v127, v19
	v_max_f32_e32 v3, 0, v3
	v_fmac_f32_e32 v26, v128, v3
	v_max_f32_e32 v3, v4, v4
	v_max_f32_e32 v3, 0, v3
	v_fmac_f32_e32 v2, v136, v3
	v_max_f32_e32 v3, v12, v12
	v_max_f32_e32 v3, 0, v3
	v_fmac_f32_e32 v10, v144, v3
	v_max_f32_e32 v3, v21, v21
	v_max_f32_e32 v3, 0, v3
	v_fmac_f32_e32 v18, v121, v3
	v_max_f32_e32 v3, v29, v29
	v_max_f32_e32 v3, 0, v3
	v_fmac_f32_e32 v26, v129, v3
	v_max_f32_e32 v3, v5, v5
	v_max_f32_e32 v3, 0, v3
	v_fmac_f32_e32 v2, v137, v3
	v_max_f32_e32 v3, v13, v13
	v_max_f32_e32 v3, 0, v3
	v_fmac_f32_e32 v10, v145, v3
	v_max_f32_e32 v3, v22, v22
	v_max_f32_e32 v3, 0, v3
	v_fmac_f32_e32 v18, v122, v3
	v_max_f32_e32 v3, v30, v30
	v_max_f32_e32 v3, 0, v3
	v_fmac_f32_e32 v26, v130, v3
	v_max_f32_e32 v3, v6, v6
	v_max_f32_e32 v3, 0, v3
	v_fmac_f32_e32 v2, v138, v3
	v_max_f32_e32 v3, v14, v14
	v_max_f32_e32 v3, 0, v3
	v_fmac_f32_e32 v10, v146, v3
	v_max_f32_e32 v3, v23, v23
	v_max_f32_e32 v3, 0, v3
	v_fmac_f32_e32 v18, v123, v3
	v_max_f32_e32 v3, v31, v31
	v_max_f32_e32 v3, 0, v3
	v_fmac_f32_e32 v26, v131, v3
	v_max_f32_e32 v3, v7, v7
	v_max_f32_e32 v3, 0, v3
	v_fmac_f32_e32 v2, v139, v3
	v_max_f32_e32 v3, v15, v15
	v_max_f32_e32 v3, 0, v3
	v_fmac_f32_e32 v10, v147, v3
	v_max_f32_e32 v3, v24, v24
	v_max_f32_e32 v3, 0, v3
	v_fmac_f32_e32 v18, v124, v3
	v_max_f32_e32 v3, v32, v32
	v_max_f32_e32 v3, 0, v3
	v_fmac_f32_e32 v26, v132, v3
	v_max_f32_e32 v3, v8, v8
	v_max_f32_e32 v3, 0, v3
	v_fmac_f32_e32 v2, v140, v3
	v_max_f32_e32 v3, v16, v16
	v_max_f32_e32 v3, 0, v3
	v_fmac_f32_e32 v10, v148, v3
	v_max_f32_e32 v3, v25, v25
	v_max_f32_e32 v3, 0, v3
	v_fmac_f32_e32 v18, v125, v3
	v_max_f32_e32 v3, v33, v33
	v_max_f32_e32 v3, 0, v3
	v_fmac_f32_e32 v26, v133, v3
	v_max_f32_e32 v3, v9, v9
	v_max_f32_e32 v3, 0, v3
	v_fmac_f32_e32 v2, v141, v3
	v_max_f32_e32 v3, v17, v17
	v_max_f32_e32 v3, 0, v3
	v_fmac_f32_e32 v10, v149, v3
	v_add_f32_e32 v3, 0, v18
	v_add_f32_e32 v4, 0, v26
	ds_write2st64_b32 v150, v3, v4 offset0:6 offset1:38
	v_add_f32_e32 v2, 0, v2
	v_add_f32_e32 v3, 0, v10
	ds_write2st64_b32 v150, v2, v3 offset0:134 offset1:166
	s_branch .LBB0_345

; DI void phaseA1(const Params& p, int vblock, int nvblocks, int ubegin, int uend, char* smem) {
;     ...
;     const int u = 4095 - u0;
;     const int b = u >> 8, q0 = (u & 255) * 8;
;     const size_t tokb = (size_t)b * SEQ;
;     const int qa = ((r >> 2) & 1) * 2 + (r >> 4), ha = (r & 3) + 4 * ((r >> 3) & 1);
;     bf16x8 af0[4], af1[4];
; #pragma unroll
;     for (int ks = 0; ks < 4; ++ks) {
;       af0[ks] = ld16(p.projA + (tokb + q0 + qa) * LDA_A + 640 + ha * 64 + ks * 16 + hh * 8);
;       af1[ks] = ld16(p.projA + (tokb + q0 + 4 + qa) * LDA_A + 640 + ha * 64 + ks * 16 + hh * 8);
;     }
;     float wr0[16], wr1[16];
;     {
;       const float4* sp = (const float4*)(p.small + (tokb + q0 + hh * 2) * 32);
;       const float4 wa = sp[0], wb = sp[1], wc = sp[8], wd = sp[9], we = sp[32], wf = sp[33], wg = sp[40], wh = sp[41];
;       __builtin_amdgcn_sched_barrier(0);
;       const float cs = 0.044194173824159216f;
;       wr0[0] = wa.x * cs; wr0[1] = wa.y * cs; wr0[2] = wa.z * cs; wr0[3] = wa.w * cs; wr0[4] = wb.x * cs; wr0[5] = wb.y * cs; wr0[6] = wb.z * cs; wr0[7] = wb.w * cs;
;       wr0[8] = wc.x * cs; wr0[9] = wc.y * cs; wr0[10] = wc.z * cs; wr0[11] = wc.w * cs; wr0[12] = wd.x * cs; wr0[13] = wd.y * cs; wr0[14] = wd.z * cs; wr0[15] = wd.w * cs;
;       wr1[0] = we.x * cs; wr1[1] = we.y * cs; wr1[2] = we.z * cs; wr1[3] = we.w * cs; wr1[4] = wf.x * cs; wr1[5] = wf.y * cs; wr1[6] = wf.z * cs; wr1[7] = wf.w * cs;
;       wr1[8] = wg.x * cs; wr1[9] = wg.y * cs; wr1[10] = wg.z * cs; wr1[11] = wg.w * cs; wr1[12] = wh.x * cs; wr1[13] = wh.y * cs; wr1[14] = wh.z * cs; wr1[15] = wh.w * cs;
;     }
;     const int nt = (q0 + 7) / 32 + 1;
;     const bf16_t* kib = p.kidxF + (size_t)b * 64 * 2048 + (hh * 32 + r) * 8;
; #pragma unroll 1
;     for (int kb = wid; kb < nt; kb += 16) {
;       bf16x8 kf[4][4];
; #pragma unroll
;       for (int j = 0; j < 4; ++j) {
;         const int kt = kb + 4 * j < nt ? kb + 4 * j : kb;
;         const bf16_t* q_ = kib + (size_t)kt * 2048;
.LBB0_802:
	s_sub_i32 s2, 0xfff, s11
	s_lshl_b32 s16, s2, 3
	s_lshr_b32 s14, s2, 8
	s_and_b32 s88, s16, 0x7f8
	v_readlane_b32 s36, v252, 57
	s_lshl_b64 s[12:13], s[14:15], 11
	v_or_b32_e32 v2, s88, v116
	v_readlane_b32 s44, v253, 1
	v_readlane_b32 s45, v253, 2
	v_or_b32_e32 v4, s12, v2
	s_movk_i32 s2, 0xd00
	v_mov_b64_e32 v[2:3], s[44:45]
	v_mad_u64_u32 v[2:3], s[2:3], v4, s2, v[2:3]
	v_mad_u32_u24 v3, s13, v238, v3
	v_lshl_add_u64 v[2:3], v[2:3], 0, v[0:1]
	v_mov_b32_e32 v111, v1
	v_lshl_add_u64 v[2:3], v[2:3], 0, v[110:111]
	s_mov_b64 s[2:3], 0x3900
	v_add_co_u32_e32 v6, vcc, s81, v2
	s_or_b32 s12, s12, s88
	v_lshl_add_u64 v[4:5], v[2:3], 0, s[2:3]
	v_addc_co_u32_e32 v7, vcc, 0, v3, vcc
	global_load_dwordx4 v[34:37], v[2:3], off offset:1280
	global_load_dwordx4 v[38:41], v[2:3], off offset:1312
	global_load_dwordx4 v[42:45], v[4:5], off offset:32
	global_load_dwordx4 v[46:49], v[4:5], off offset:64
	global_load_dwordx4 v[50:53], v[2:3], off offset:1344
	global_load_dwordx4 v[54:57], v[2:3], off offset:1376
	global_load_dwordx4 v[58:61], v[6:7], off offset:2304
	global_load_dwordx4 v[62:65], v[4:5], off offset:96
	v_mov_b32_e32 v3, s13
	v_or_b32_e32 v2, s12, v100
	v_readlane_b32 s50, v253, 7
	v_readlane_b32 s51, v253, 8
	v_lshlrev_b64 v[2:3], 7, v[2:3]
	v_readlane_b32 s40, v252, 61
	v_lshl_add_u64 v[6:7], s[50:51], 0, v[2:3]
	global_load_dwordx4 v[26:29], v[6:7], off offset:16
	global_load_dwordx4 v[30:33], v[6:7], off
	global_load_dwordx4 v[18:21], v[6:7], off offset:144
	global_load_dwordx4 v[22:25], v[6:7], off offset:128
	global_load_dwordx4 v[10:13], v[6:7], off offset:528
	global_load_dwordx4 v[14:17], v[6:7], off offset:512
	global_load_dwordx4 v[2:5], v[6:7], off offset:656
	s_nop 0
	global_load_dwordx4 v[6:9], v[6:7], off offset:640
	v_readlane_b32 s41, v252, 62
	v_readlane_b32 s42, v252, 63
	s_movk_i32 s42, 0x100
	s_mov_b64 s[40:41], 0x10000
	v_readlane_b32 s37, v252, 58
	v_readlane_b32 s38, v252, 59
	v_readlane_b32 s39, v252, 60
	v_readlane_b32 s43, v253, 0
	v_readlane_b32 s46, v253, 3
	v_readlane_b32 s47, v253, 4
	v_readlane_b32 s48, v253, 5
	v_readlane_b32 s49, v253, 6
	s_bfe_u32 s89, s16, 0x60005
	v_cmp_ge_i32_e32 vcc, s89, v98
	s_and_saveexec_b64 s[84:85], vcc
	s_mov_b32 s18, 0xff00ff
	s_mov_b32 s19, 0xf0f0f0f
	s_mov_b32 s20, 0x33333333
	s_mov_b32 s21, 0x55555555
	s_cbranch_execz .LBB0_811
	s_lshl_b64 s[2:3], s[10:11], 10
	s_and_b32 s3, s3, 0x3ff
	s_and_b32 s2, s2, 0xfffc0000
	v_lshl_add_u64 v[112:113], v[108:109], 0, s[2:3]
	global_load_dwordx4 v[216:219], v[112:113], off offset:-3072
	global_load_dwordx4 v[220:223], v[112:113], off offset:-2048
	global_load_dwordx4 v[224:227], v[112:113], off offset:-1024
	global_load_dwordx4 v[240:243], v[112:113], off
	s_lshl_b64 s[2:3], s[14:15], 18
	s_waitcnt vmcnt(10)
	v_mul_f32_e32 v111, 0x3d3504f3, v30
	v_mul_f32_e32 v119, 0x3d3504f3, v31
	v_mul_f32_e32 v120, 0x3d3504f3, v32
	v_mul_f32_e32 v121, 0x3d3504f3, v33
	v_mul_f32_e32 v122, 0x3d3504f3, v26
	v_mul_f32_e32 v123, 0x3d3504f3, v27
	v_mul_f32_e32 v124, 0x3d3504f3, v28
	v_mul_f32_e32 v125, 0x3d3504f3, v29
	s_waitcnt vmcnt(8)
	v_mul_f32_e32 v126, 0x3d3504f3, v22
	v_mul_f32_e32 v127, 0x3d3504f3, v23
	v_mul_f32_e32 v128, 0x3d3504f3, v24
	v_mul_f32_e32 v129, 0x3d3504f3, v25
	v_mul_f32_e32 v130, 0x3d3504f3, v18
	v_mul_f32_e32 v131, 0x3d3504f3, v19
	v_mul_f32_e32 v132, 0x3d3504f3, v20
	v_mul_f32_e32 v133, 0x3d3504f3, v21
	s_waitcnt vmcnt(6)
	v_mul_f32_e32 v134, 0x3d3504f3, v14
	v_mul_f32_e32 v135, 0x3d3504f3, v15
	v_mul_f32_e32 v136, 0x3d3504f3, v16
	v_mul_f32_e32 v137, 0x3d3504f3, v17
	v_mul_f32_e32 v138, 0x3d3504f3, v10
	v_mul_f32_e32 v139, 0x3d3504f3, v11
	v_mul_f32_e32 v140, 0x3d3504f3, v12
	v_mul_f32_e32 v141, 0x3d3504f3, v13
	s_waitcnt vmcnt(4)
	v_mul_f32_e32 v142, 0x3d3504f3, v6
	v_mul_f32_e32 v143, 0x3d3504f3, v7
	v_mul_f32_e32 v144, 0x3d3504f3, v8
	v_mul_f32_e32 v145, 0x3d3504f3, v9
	v_mul_f32_e32 v146, 0x3d3504f3, v2
	v_mul_f32_e32 v147, 0x3d3504f3, v3
	v_mul_f32_e32 v148, 0x3d3504f3, v4
	v_mul_f32_e32 v149, 0x3d3504f3, v5
	v_lshl_add_u64 v[114:115], v[104:105], 0, s[2:3]
	s_mov_b64 s[86:87], 0
	v_mov_b32_e32 v150, v118
	v_mov_b32_e32 v151, v98
	s_branch .LBB0_805

; DI void phaseA1(const Params& p, int vblock, int nvblocks, int ubegin, int uend, char* smem) {
;     ...
;     const int u = 4095 - u0;
;     const int b = u >> 8, q0 = (u & 255) * 8;
;     const size_t tokb = (size_t)b * SEQ;
;     const int qa = ((r >> 2) & 1) * 2 + (r >> 4), ha = (r & 3) + 4 * ((r >> 3) & 1);
;     bf16x8 af0[4], af1[4];
; #pragma unroll
;     for (int ks = 0; ks < 4; ++ks) {
;       af0[ks] = ld16(p.projA + (tokb + q0 + qa) * LDA_A + 640 + ha * 64 + ks * 16 + hh * 8);
;       af1[ks] = ld16(p.projA + (tokb + q0 + 4 + qa) * LDA_A + 640 + ha * 64 + ks * 16 + hh * 8);
;     }
;     float wr0[16], wr1[16];
;     {
;       const float4* sp = (const float4*)(p.small + (tokb + q0 + hh * 2) * 32);
;       const float4 wa = sp[0], wb = sp[1], wc = sp[8], wd = sp[9], we = sp[32], wf = sp[33], wg = sp[40], wh = sp[41];
;       __builtin_amdgcn_sched_barrier(0);
;       const float cs = 0.044194173824159216f;
;       wr0[0] = wa.x * cs; wr0[1] = wa.y * cs; wr0[2] = wa.z * cs; wr0[3] = wa.w * cs; wr0[4] = wb.x * cs; wr0[5] = wb.y * cs; wr0[6] = wb.z * cs; wr0[7] = wb.w * cs;
;       wr0[8] = wc.x * cs; wr0[9] = wc.y * cs; wr0[10] = wc.z * cs; wr0[11] = wc.w * cs; wr0[12] = wd.x * cs; wr0[13] = wd.y * cs; wr0[14] = wd.z * cs; wr0[15] = wd.w * cs;
;       wr1[0] = we.x * cs; wr1[1] = we.y * cs; wr1[2] = we.z * cs; wr1[3] = we.w * cs; wr1[4] = wf.x * cs; wr1[5] = wf.y * cs; wr1[6] = wf.z * cs; wr1[7] = wf.w * cs;
;       wr1[8] = wg.x * cs; wr1[9] = wg.y * cs; wr1[10] = wg.z * cs; wr1[11] = wg.w * cs; wr1[12] = wh.x * cs; wr1[13] = wh.y * cs; wr1[14] = wh.z * cs; wr1[15] = wh.w * cs;
;     }
;     const int nt = (q0 + 7) / 32 + 1;
;     const bf16_t* kib = p.kidxF + (size_t)b * 64 * 2048 + (hh * 32 + r) * 8;
; #pragma unroll 1
;     for (int kb = wid; kb < nt; kb += 16) {
;       bf16x8 kf[4][4];
; #pragma unroll
;       for (int j = 0; j < 4; ++j) {
;         const int kt = kb + 4 * j < nt ? kb + 4 * j : kb;
;         const bf16_t* q_ = kib + (size_t)kt * 2048;
.LBB0_1320:
	s_sub_i32 s2, 0xfff, s11
	s_lshl_b32 s16, s2, 3
	s_lshr_b32 s14, s2, 8
	s_and_b32 s88, s16, 0x7f8
	v_readlane_b32 s36, v252, 57
	s_lshl_b64 s[12:13], s[14:15], 11
	v_or_b32_e32 v2, s88, v116
	v_readlane_b32 s44, v253, 1
	v_readlane_b32 s45, v253, 2
	v_or_b32_e32 v4, s12, v2
	s_movk_i32 s2, 0xd00
	v_mov_b64_e32 v[2:3], s[44:45]
	v_mad_u64_u32 v[2:3], s[2:3], v4, s2, v[2:3]
	v_mad_u32_u24 v3, s13, v238, v3
	v_lshl_add_u64 v[2:3], v[2:3], 0, v[0:1]
	v_mov_b32_e32 v111, v1
	v_lshl_add_u64 v[2:3], v[2:3], 0, v[110:111]
	s_mov_b64 s[2:3], 0x3900
	v_add_co_u32_e32 v6, vcc, s81, v2
	s_or_b32 s12, s12, s88
	v_lshl_add_u64 v[4:5], v[2:3], 0, s[2:3]
	v_addc_co_u32_e32 v7, vcc, 0, v3, vcc
	global_load_dwordx4 v[34:37], v[2:3], off offset:1280
	global_load_dwordx4 v[38:41], v[2:3], off offset:1312
	global_load_dwordx4 v[42:45], v[4:5], off offset:32
	global_load_dwordx4 v[46:49], v[4:5], off offset:64
	global_load_dwordx4 v[50:53], v[2:3], off offset:1344
	global_load_dwordx4 v[54:57], v[2:3], off offset:1376
	global_load_dwordx4 v[58:61], v[6:7], off offset:2304
	global_load_dwordx4 v[62:65], v[4:5], off offset:96
	v_mov_b32_e32 v3, s13
	v_or_b32_e32 v2, s12, v100
	v_readlane_b32 s50, v253, 7
	v_readlane_b32 s51, v253, 8
	v_lshlrev_b64 v[2:3], 7, v[2:3]
	v_readlane_b32 s40, v252, 61
	v_lshl_add_u64 v[6:7], s[50:51], 0, v[2:3]
	global_load_dwordx4 v[26:29], v[6:7], off offset:16
	global_load_dwordx4 v[30:33], v[6:7], off
	global_load_dwordx4 v[18:21], v[6:7], off offset:144
	global_load_dwordx4 v[22:25], v[6:7], off offset:128
	global_load_dwordx4 v[10:13], v[6:7], off offset:528
	global_load_dwordx4 v[14:17], v[6:7], off offset:512
	global_load_dwordx4 v[2:5], v[6:7], off offset:656
	s_nop 0
	global_load_dwordx4 v[6:9], v[6:7], off offset:640
	v_readlane_b32 s41, v252, 62
	v_readlane_b32 s42, v252, 63
	s_movk_i32 s42, 0x100
	s_mov_b64 s[40:41], 0x10000
	v_readlane_b32 s37, v252, 58
	v_readlane_b32 s38, v252, 59
	v_readlane_b32 s39, v252, 60
	v_readlane_b32 s43, v253, 0
	v_readlane_b32 s46, v253, 3
	v_readlane_b32 s47, v253, 4
	v_readlane_b32 s48, v253, 5
	v_readlane_b32 s49, v253, 6
	s_bfe_u32 s89, s16, 0x60005
	v_cmp_ge_i32_e32 vcc, s89, v98
	s_and_saveexec_b64 s[84:85], vcc
	s_mov_b32 s19, 0xff00ff
	s_mov_b32 s20, 0xf0f0f0f
	s_mov_b32 s21, 0x33333333
	s_mov_b32 s22, 0x55555555
	s_cbranch_execz .LBB0_1329
	s_lshl_b64 s[2:3], s[10:11], 10
	s_and_b32 s3, s3, 0x3ff
	s_and_b32 s2, s2, 0xfffc0000
	v_lshl_add_u64 v[112:113], v[108:109], 0, s[2:3]
	global_load_dwordx4 v[216:219], v[112:113], off offset:-3072
	global_load_dwordx4 v[220:223], v[112:113], off offset:-2048
	global_load_dwordx4 v[224:227], v[112:113], off offset:-1024
	global_load_dwordx4 v[240:243], v[112:113], off
	s_lshl_b64 s[2:3], s[14:15], 18
	s_waitcnt vmcnt(10)
	v_mul_f32_e32 v111, 0x3d3504f3, v30
	v_mul_f32_e32 v119, 0x3d3504f3, v31
	v_mul_f32_e32 v120, 0x3d3504f3, v32
	v_mul_f32_e32 v121, 0x3d3504f3, v33
	v_mul_f32_e32 v122, 0x3d3504f3, v26
	v_mul_f32_e32 v123, 0x3d3504f3, v27
	v_mul_f32_e32 v124, 0x3d3504f3, v28
	v_mul_f32_e32 v125, 0x3d3504f3, v29
	s_waitcnt vmcnt(8)
	v_mul_f32_e32 v126, 0x3d3504f3, v22
	v_mul_f32_e32 v127, 0x3d3504f3, v23
	v_mul_f32_e32 v128, 0x3d3504f3, v24
	v_mul_f32_e32 v129, 0x3d3504f3, v25
	v_mul_f32_e32 v130, 0x3d3504f3, v18
	v_mul_f32_e32 v131, 0x3d3504f3, v19
	v_mul_f32_e32 v132, 0x3d3504f3, v20
	v_mul_f32_e32 v133, 0x3d3504f3, v21
	s_waitcnt vmcnt(6)
	v_mul_f32_e32 v134, 0x3d3504f3, v14
	v_mul_f32_e32 v135, 0x3d3504f3, v15
	v_mul_f32_e32 v136, 0x3d3504f3, v16
	v_mul_f32_e32 v137, 0x3d3504f3, v17
	v_mul_f32_e32 v138, 0x3d3504f3, v10
	v_mul_f32_e32 v139, 0x3d3504f3, v11
	v_mul_f32_e32 v140, 0x3d3504f3, v12
	v_mul_f32_e32 v141, 0x3d3504f3, v13
	s_waitcnt vmcnt(4)
	v_mul_f32_e32 v142, 0x3d3504f3, v6
	v_mul_f32_e32 v143, 0x3d3504f3, v7
	v_mul_f32_e32 v144, 0x3d3504f3, v8
	v_mul_f32_e32 v145, 0x3d3504f3, v9
	v_mul_f32_e32 v146, 0x3d3504f3, v2
	v_mul_f32_e32 v147, 0x3d3504f3, v3
	v_mul_f32_e32 v148, 0x3d3504f3, v4
	v_mul_f32_e32 v149, 0x3d3504f3, v5
	v_lshl_add_u64 v[114:115], v[104:105], 0, s[2:3]
	s_mov_b64 s[86:87], 0
	v_mov_b32_e32 v150, v118
	v_mov_b32_e32 v151, v98
	s_branch .LBB0_1323
